# speedup vs baseline: 1.0484x; 1.0084x over previous
; DEV void hyena_item(const Params& p, int layer, int item, char* smem) {
;     ...
; #pragma unroll 8
;   for (int j = 0; j < 32; ++j) {
;     int i = tid + 256 * j;
;     buf[fphys(i)] = cmul(buf[fphys(i)], K0[i]);
;   }
.LBB0_434:
	v_add_u32_e32 v17, s4, v8
	global_load_dwordx2 v[36:37], v[26:27], off offset:-2048
	global_load_dwordx2 v[38:39], v[26:27], off
	v_add_u32_e32 v28, 0x200, v17
	v_ashrrev_i32_e32 v29, 31, v28
	v_lshl_add_u64 v[28:29], v[28:29], 3, s[0:1]
	global_load_dwordx2 v[40:41], v[28:29], off
	v_add_u32_e32 v28, 0x300, v17
	v_ashrrev_i32_e32 v29, 31, v28
	v_lshl_add_u64 v[28:29], v[28:29], 3, s[0:1]
	global_load_dwordx2 v[42:43], v[28:29], off
	v_add_u32_e32 v28, 0x400, v17
	v_ashrrev_i32_e32 v29, 31, v28
	v_lshl_add_u64 v[28:29], v[28:29], 3, s[0:1]
	global_load_dwordx2 v[44:45], v[28:29], off
	v_add_u32_e32 v28, 0x500, v17
	v_ashrrev_i32_e32 v29, 31, v28
	v_lshl_add_u64 v[28:29], v[28:29], 3, s[0:1]
	global_load_dwordx2 v[46:47], v[28:29], off
	v_add_u32_e32 v28, 0x600, v17
	v_ashrrev_i32_e32 v29, 31, v28
	v_lshl_add_u64 v[28:29], v[28:29], 3, s[0:1]
	global_load_dwordx2 v[48:49], v[28:29], off
	v_add_u32_e32 v28, 0x700, v17
	v_ashrrev_i32_e32 v29, 31, v28
	v_lshl_add_u64 v[28:29], v[28:29], 3, s[0:1]
	global_load_dwordx2 v[50:51], v[28:29], off
	v_lshl_add_u64 v[26:27], v[26:27], 0, s[6:7]
	s_addk_i32 s4, 0x800
	s_cmpk_eq_i32 s4, 0x2000
	v_and_b32_e32 v19, -8, v17
	v_add_u32_e32 v19, v9, v19
	ds_read_b64 v[30:31], v19
	s_waitcnt vmcnt(0)
	v_add_u32_e32 v54, 0x100, v17
	v_and_b32_e32 v54, -8, v54
	v_add_u32_e32 v54, v9, v54
	ds_read_b64 v[52:53], v54 offset:2048
	s_waitcnt lgkmcnt(1)
	v_pk_mul_f32 v[32:33], v[30:31], v[36:37] op_sel:[1,1] op_sel_hi:[0,1]
	v_pk_fma_f32 v[34:35], v[30:31], v[36:37], v[32:33] neg_lo:[0,0,1] neg_hi:[0,0,1]
	v_pk_fma_f32 v[28:29], v[30:31], v[36:37], v[32:33] op_sel_hi:[1,0,1]
	s_nop 0
	v_mov_b32_e32 v35, v29
	ds_write_b64 v19, v[34:35]
	v_add_u32_e32 v19, 0x200, v17
	v_and_b32_e32 v19, -8, v19
	v_add_u32_e32 v19, v9, v19
	ds_read_b64 v[30:31], v19 offset:4096
	s_waitcnt lgkmcnt(2)
	v_pk_mul_f32 v[32:33], v[52:53], v[38:39] op_sel:[1,1] op_sel_hi:[0,1]
	v_pk_fma_f32 v[56:57], v[52:53], v[38:39], v[32:33] neg_lo:[0,0,1] neg_hi:[0,0,1]
	v_pk_fma_f32 v[28:29], v[52:53], v[38:39], v[32:33] op_sel_hi:[1,0,1]
	s_nop 0
	v_mov_b32_e32 v57, v29
	ds_write_b64 v54, v[56:57] offset:2048
	v_add_u32_e32 v54, 0x300, v17
	v_and_b32_e32 v54, -8, v54
	v_add_u32_e32 v54, v9, v54
	ds_read_b64 v[52:53], v54 offset:6144
	s_waitcnt lgkmcnt(2)
	v_pk_mul_f32 v[32:33], v[30:31], v[40:41] op_sel:[1,1] op_sel_hi:[0,1]
	v_pk_fma_f32 v[34:35], v[30:31], v[40:41], v[32:33] neg_lo:[0,0,1] neg_hi:[0,0,1]
	v_pk_fma_f32 v[28:29], v[30:31], v[40:41], v[32:33] op_sel_hi:[1,0,1]
	s_nop 0
	v_mov_b32_e32 v35, v29
	ds_write_b64 v19, v[34:35] offset:4096
	v_add_u32_e32 v19, 0x400, v17
	v_and_b32_e32 v19, -8, v19
	v_add_u32_e32 v19, v9, v19
	ds_read_b64 v[30:31], v19 offset:8192
	s_waitcnt lgkmcnt(2)
	v_pk_mul_f32 v[32:33], v[52:53], v[42:43] op_sel:[1,1] op_sel_hi:[0,1]
	v_pk_fma_f32 v[56:57], v[52:53], v[42:43], v[32:33] neg_lo:[0,0,1] neg_hi:[0,0,1]
	v_pk_fma_f32 v[28:29], v[52:53], v[42:43], v[32:33] op_sel_hi:[1,0,1]
	s_nop 0
	v_mov_b32_e32 v57, v29
	ds_write_b64 v54, v[56:57] offset:6144
	v_add_u32_e32 v54, 0x500, v17
	v_and_b32_e32 v54, -8, v54
	v_add_u32_e32 v54, v9, v54
	ds_read_b64 v[52:53], v54 offset:10240
	s_waitcnt lgkmcnt(2)
	v_pk_mul_f32 v[32:33], v[30:31], v[44:45] op_sel:[1,1] op_sel_hi:[0,1]
	v_pk_fma_f32 v[34:35], v[30:31], v[44:45], v[32:33] neg_lo:[0,0,1] neg_hi:[0,0,1]
	v_pk_fma_f32 v[28:29], v[30:31], v[44:45], v[32:33] op_sel_hi:[1,0,1]
	s_nop 0
	v_mov_b32_e32 v35, v29
	ds_write_b64 v19, v[34:35] offset:8192
	v_add_u32_e32 v19, 0x600, v17
	v_and_b32_e32 v19, -8, v19
	v_add_u32_e32 v19, v9, v19
	ds_read_b64 v[30:31], v19 offset:12288
	s_waitcnt lgkmcnt(2)
	v_pk_mul_f32 v[32:33], v[52:53], v[46:47] op_sel:[1,1] op_sel_hi:[0,1]
	v_pk_fma_f32 v[56:57], v[52:53], v[46:47], v[32:33] neg_lo:[0,0,1] neg_hi:[0,0,1]
	v_pk_fma_f32 v[28:29], v[52:53], v[46:47], v[32:33] op_sel_hi:[1,0,1]
	s_nop 0
	v_mov_b32_e32 v57, v29
	ds_write_b64 v54, v[56:57] offset:10240
	v_add_u32_e32 v54, 0x700, v17
	v_and_b32_e32 v54, -8, v54
	v_add_u32_e32 v54, v9, v54
	ds_read_b64 v[52:53], v54 offset:14336
	s_waitcnt lgkmcnt(2)
	v_pk_mul_f32 v[32:33], v[30:31], v[48:49] op_sel:[1,1] op_sel_hi:[0,1]
	v_pk_fma_f32 v[34:35], v[30:31], v[48:49], v[32:33] neg_lo:[0,0,1] neg_hi:[0,0,1]
	v_pk_fma_f32 v[28:29], v[30:31], v[48:49], v[32:33] op_sel_hi:[1,0,1]
	s_nop 0
	v_mov_b32_e32 v35, v29
	ds_write_b64 v19, v[34:35] offset:12288
	s_waitcnt lgkmcnt(1)
	v_pk_mul_f32 v[32:33], v[52:53], v[50:51] op_sel:[1,1] op_sel_hi:[0,1]
	v_pk_fma_f32 v[56:57], v[52:53], v[50:51], v[32:33] neg_lo:[0,0,1] neg_hi:[0,0,1]
	v_pk_fma_f32 v[28:29], v[52:53], v[50:51], v[32:33] op_sel_hi:[1,0,1]
	s_nop 0
	v_mov_b32_e32 v57, v29
	ds_write_b64 v54, v[56:57] offset:14336
	v_add_u32_e32 v9, 0x4000, v9
	s_cbranch_scc0 .LBB0_434
; template <int R, bool INV>
; DEV void fft_pass(cf* buf, int s_log2, int tid) {
;   constexpr int RAD = 1 << R;
;   const int s = 1 << s_log2;
;   const int ngroups = FFT_N >> R;
;   for (int gi = tid; gi < ngroups; gi += 256) {
;     int hi = gi >> s_log2, lo = gi & (s - 1);
;     int base = (hi << (s_log2 + R)) + lo;
;     cf v[RAD];
; #pragma unroll
;     for (int k = 0; k < RAD; ++k) v[k] = buf[fphys(base + (k << s_log2))];
; DEV void hyena_item(const Params& p, int layer, int item, char* smem) {
;     ...
;   __syncthreads();
;   fft_inv(buf, tid);
	s_waitcnt lgkmcnt(0)
	s_barrier
	s_and_saveexec_b64 s[60:61], s[2:3]
	s_cbranch_execz .LBB0_445
	v_add_u32_e32 v9, 0xff, v65
	s_movk_i32 s0, 0x2100
	s_movk_i32 s4, 0x20ff
	v_cmp_gt_u32_e64 s[0:1], s0, v9
	v_cmp_lt_u32_e64 s[4:5], s4, v9
	v_mov_b32_e32 v21, v8
	s_and_saveexec_b64 s[20:21], s[4:5]
	s_cbranch_execz .LBB0_442
	v_lshrrev_b32_e32 v9, 8, v9
	s_movk_i32 s4, 0x48
	v_mul_lo_u32 v17, v8, s4
	v_mul_hi_u32_u24_e32 v19, 0x4800, v9
	s_movk_i32 s6, 0x4800
	v_cmp_ne_u32_e64 s[4:5], 0, v19
	v_mad_u32_u24 v19, v9, s6, v17
	v_cmp_lt_u32_e64 s[6:7], v19, v17
	v_add_u32_e32 v21, 8, v17
	v_add_u32_e32 v23, 8, v19
	s_or_b64 s[22:23], s[6:7], s[4:5]
	v_cmp_lt_u32_e64 s[6:7], v23, v21
	v_add_u32_e32 v21, 12, v17
	v_add_u32_e32 v23, 12, v19
	s_or_b64 s[24:25], s[6:7], s[4:5]
	v_cmp_lt_u32_e64 s[6:7], v23, v21
	v_add_u32_e32 v21, 16, v17
	v_add_u32_e32 v23, 16, v19
	s_or_b64 s[28:29], s[6:7], s[4:5]
	v_cmp_lt_u32_e64 s[6:7], v23, v21
	v_add_u32_e32 v21, 20, v17
	v_add_u32_e32 v23, 20, v19
	s_or_b64 s[30:31], s[6:7], s[4:5]
	v_cmp_lt_u32_e64 s[6:7], v23, v21
	v_add_u32_e32 v21, 24, v17
	v_add_u32_e32 v23, 24, v19
	s_or_b64 s[36:37], s[6:7], s[4:5]
	v_cmp_lt_u32_e64 s[6:7], v23, v21
	v_add_u32_e32 v21, 28, v17
	v_add_u32_e32 v23, 28, v19
	s_or_b64 s[38:39], s[6:7], s[4:5]
	v_cmp_lt_u32_e64 s[6:7], v23, v21
	v_add_u32_e32 v21, 32, v17
	v_add_u32_e32 v23, 32, v19
	s_or_b64 s[40:41], s[6:7], s[4:5]
	v_cmp_lt_u32_e64 s[6:7], v23, v21
	v_add_u32_e32 v21, 36, v17
	v_add_u32_e32 v23, 36, v19
	s_or_b64 s[42:43], s[6:7], s[4:5]
	v_cmp_lt_u32_e64 s[6:7], v23, v21
	v_add_u32_e32 v21, 40, v17
	v_add_u32_e32 v23, 40, v19
	s_or_b64 s[44:45], s[6:7], s[4:5]
	v_cmp_lt_u32_e64 s[6:7], v23, v21
	v_add_u32_e32 v21, 44, v17
	v_add_u32_e32 v23, 44, v19
	s_or_b64 s[46:47], s[6:7], s[4:5]
	v_cmp_lt_u32_e64 s[6:7], v23, v21
	v_add_u32_e32 v21, 48, v17
	v_add_u32_e32 v23, 48, v19
	s_or_b64 s[48:49], s[6:7], s[4:5]
	v_cmp_lt_u32_e64 s[6:7], v23, v21
	v_add_u32_e32 v21, 52, v17
	v_add_u32_e32 v23, 52, v19
	s_or_b64 s[50:51], s[6:7], s[4:5]
	v_cmp_lt_u32_e64 s[6:7], v23, v21
	v_add_u32_e32 v21, 56, v17
	v_add_u32_e32 v23, 56, v19
	s_or_b64 s[92:93], s[6:7], s[4:5]
	v_cmp_lt_u32_e64 s[6:7], v23, v21
	v_add_u32_e32 v17, 60, v17
	v_add_u32_e32 v19, 60, v19
	s_or_b64 s[96:97], s[6:7], s[4:5]
	v_cmp_lt_u32_e64 s[6:7], v19, v17
	s_or_b64 s[4:5], s[6:7], s[4:5]
	s_or_b64 s[6:7], s[22:23], s[24:25]
	s_or_b64 s[6:7], s[6:7], s[28:29]
	s_or_b64 s[6:7], s[6:7], s[30:31]
	s_or_b64 s[6:7], s[6:7], s[36:37]
	s_or_b64 s[6:7], s[6:7], s[38:39]
	s_or_b64 s[6:7], s[6:7], s[40:41]
	s_or_b64 s[6:7], s[6:7], s[42:43]
	s_or_b64 s[6:7], s[6:7], s[44:45]
	s_or_b64 s[6:7], s[6:7], s[46:47]
	s_or_b64 s[6:7], s[6:7], s[48:49]
	s_or_b64 s[6:7], s[6:7], s[50:51]
	s_or_b64 s[6:7], s[6:7], s[92:93]
	s_or_b64 s[6:7], s[6:7], s[96:97]
	s_nor_b64 s[22:23], s[6:7], s[4:5]
	s_mov_b64 s[4:5], -1
	v_mov_b32_e32 v21, v8
	s_and_saveexec_b64 s[6:7], s[22:23]
	s_cbranch_execz .LBB0_441
	v_add_u32_e32 v17, 1, v9
	v_and_b32_e32 v19, 0x1fffffe, v17
	v_add_u32_e32 v9, 0x100, v8
	s_mov_b64 s[22:23], 0
	v_mov_b32_e32 v21, v19
	v_mov_b64_e32 v[26:27], v[8:9]

; DEV void hyena_item(const Params& p, int layer, int item, char* smem) {
;     ...
; #pragma unroll 8
;   for (int j = 0; j < 32; ++j) {
;     int i = tid + 256 * j;
;     buf[fphys(i)] = cmul(buf[fphys(i)], K1[i]);
;   }
.LBB0_476:
	v_add_u32_e32 v20, s4, v8
	global_load_dwordx2 v[36:37], v[10:11], off offset:-2052
	global_load_dwordx2 v[38:39], v[10:11], off offset:-4
	v_add_u32_e32 v12, 0x200, v20
	v_ashrrev_i32_e32 v13, 31, v12
	v_lshl_add_u64 v[12:13], v[12:13], 3, s[0:1]
	global_load_dwordx2 v[40:41], v[12:13], off
	v_add_u32_e32 v12, 0x300, v20
	v_ashrrev_i32_e32 v13, 31, v12
	v_lshl_add_u64 v[12:13], v[12:13], 3, s[0:1]
	global_load_dwordx2 v[42:43], v[12:13], off
	v_add_u32_e32 v12, 0x400, v20
	v_ashrrev_i32_e32 v13, 31, v12
	v_lshl_add_u64 v[12:13], v[12:13], 3, s[0:1]
	global_load_dwordx2 v[44:45], v[12:13], off
	v_add_u32_e32 v12, 0x500, v20
	v_ashrrev_i32_e32 v13, 31, v12
	v_lshl_add_u64 v[12:13], v[12:13], 3, s[0:1]
	global_load_dwordx2 v[46:47], v[12:13], off
	v_add_u32_e32 v12, 0x600, v20
	v_ashrrev_i32_e32 v13, 31, v12
	v_lshl_add_u64 v[12:13], v[12:13], 3, s[0:1]
	global_load_dwordx2 v[48:49], v[12:13], off
	v_add_u32_e32 v12, 0x700, v20
	v_ashrrev_i32_e32 v13, 31, v12
	v_lshl_add_u64 v[12:13], v[12:13], 3, s[0:1]
	global_load_dwordx2 v[50:51], v[12:13], off
	v_lshl_add_u64 v[10:11], v[10:11], 0, s[6:7]
	s_addk_i32 s4, 0x800
	s_cmpk_eq_i32 s4, 0x2000
	v_and_b32_e32 v21, -8, v20
	v_add_u32_e32 v21, v9, v21
	ds_read_b64 v[14:15], v21
	s_waitcnt vmcnt(0)
	v_add_u32_e32 v54, 0x100, v20
	v_and_b32_e32 v54, -8, v54
	v_add_u32_e32 v54, v9, v54
	ds_read_b64 v[52:53], v54 offset:2048
	s_waitcnt lgkmcnt(1)
	v_pk_mul_f32 v[16:17], v[14:15], v[36:37] op_sel:[1,1] op_sel_hi:[0,1]
	v_pk_fma_f32 v[18:19], v[14:15], v[36:37], v[16:17] neg_lo:[0,0,1] neg_hi:[0,0,1]
	v_pk_fma_f32 v[12:13], v[14:15], v[36:37], v[16:17] op_sel_hi:[1,0,1]
	s_nop 0
	v_mov_b32_e32 v19, v13
	ds_write_b64 v21, v[18:19]
	v_add_u32_e32 v21, 0x200, v20
	v_and_b32_e32 v21, -8, v21
	v_add_u32_e32 v21, v9, v21
	ds_read_b64 v[14:15], v21 offset:4096
	s_waitcnt lgkmcnt(2)
	v_pk_mul_f32 v[16:17], v[52:53], v[38:39] op_sel:[1,1] op_sel_hi:[0,1]
	v_pk_fma_f32 v[56:57], v[52:53], v[38:39], v[16:17] neg_lo:[0,0,1] neg_hi:[0,0,1]
	v_pk_fma_f32 v[12:13], v[52:53], v[38:39], v[16:17] op_sel_hi:[1,0,1]
	s_nop 0
	v_mov_b32_e32 v57, v13
	ds_write_b64 v54, v[56:57] offset:2048
	v_add_u32_e32 v54, 0x300, v20
	v_and_b32_e32 v54, -8, v54
	v_add_u32_e32 v54, v9, v54
	ds_read_b64 v[52:53], v54 offset:6144
	s_waitcnt lgkmcnt(2)
	v_pk_mul_f32 v[16:17], v[14:15], v[40:41] op_sel:[1,1] op_sel_hi:[0,1]
	v_pk_fma_f32 v[18:19], v[14:15], v[40:41], v[16:17] neg_lo:[0,0,1] neg_hi:[0,0,1]
	v_pk_fma_f32 v[12:13], v[14:15], v[40:41], v[16:17] op_sel_hi:[1,0,1]
	s_nop 0
	v_mov_b32_e32 v19, v13
	ds_write_b64 v21, v[18:19] offset:4096
	v_add_u32_e32 v21, 0x400, v20
	v_and_b32_e32 v21, -8, v21
	v_add_u32_e32 v21, v9, v21
	ds_read_b64 v[14:15], v21 offset:8192
	s_waitcnt lgkmcnt(2)
	v_pk_mul_f32 v[16:17], v[52:53], v[42:43] op_sel:[1,1] op_sel_hi:[0,1]
	v_pk_fma_f32 v[56:57], v[52:53], v[42:43], v[16:17] neg_lo:[0,0,1] neg_hi:[0,0,1]
	v_pk_fma_f32 v[12:13], v[52:53], v[42:43], v[16:17] op_sel_hi:[1,0,1]
	s_nop 0
	v_mov_b32_e32 v57, v13
	ds_write_b64 v54, v[56:57] offset:6144
	v_add_u32_e32 v54, 0x500, v20
	v_and_b32_e32 v54, -8, v54
	v_add_u32_e32 v54, v9, v54
	ds_read_b64 v[52:53], v54 offset:10240
	s_waitcnt lgkmcnt(2)
	v_pk_mul_f32 v[16:17], v[14:15], v[44:45] op_sel:[1,1] op_sel_hi:[0,1]
	v_pk_fma_f32 v[18:19], v[14:15], v[44:45], v[16:17] neg_lo:[0,0,1] neg_hi:[0,0,1]
	v_pk_fma_f32 v[12:13], v[14:15], v[44:45], v[16:17] op_sel_hi:[1,0,1]
	s_nop 0
	v_mov_b32_e32 v19, v13
	ds_write_b64 v21, v[18:19] offset:8192
	v_add_u32_e32 v21, 0x600, v20
	v_and_b32_e32 v21, -8, v21
	v_add_u32_e32 v21, v9, v21
	ds_read_b64 v[14:15], v21 offset:12288
	s_waitcnt lgkmcnt(2)
	v_pk_mul_f32 v[16:17], v[52:53], v[46:47] op_sel:[1,1] op_sel_hi:[0,1]
	v_pk_fma_f32 v[56:57], v[52:53], v[46:47], v[16:17] neg_lo:[0,0,1] neg_hi:[0,0,1]
	v_pk_fma_f32 v[12:13], v[52:53], v[46:47], v[16:17] op_sel_hi:[1,0,1]
	s_nop 0
	v_mov_b32_e32 v57, v13
	ds_write_b64 v54, v[56:57] offset:10240
	v_add_u32_e32 v54, 0x700, v20
	v_and_b32_e32 v54, -8, v54
	v_add_u32_e32 v54, v9, v54
	ds_read_b64 v[52:53], v54 offset:14336
	s_waitcnt lgkmcnt(2)
	v_pk_mul_f32 v[16:17], v[14:15], v[48:49] op_sel:[1,1] op_sel_hi:[0,1]
	v_pk_fma_f32 v[18:19], v[14:15], v[48:49], v[16:17] neg_lo:[0,0,1] neg_hi:[0,0,1]
	v_pk_fma_f32 v[12:13], v[14:15], v[48:49], v[16:17] op_sel_hi:[1,0,1]
	s_nop 0
	v_mov_b32_e32 v19, v13
	ds_write_b64 v21, v[18:19] offset:12288
	s_waitcnt lgkmcnt(1)
	v_pk_mul_f32 v[16:17], v[52:53], v[50:51] op_sel:[1,1] op_sel_hi:[0,1]
	v_pk_fma_f32 v[56:57], v[52:53], v[50:51], v[16:17] neg_lo:[0,0,1] neg_hi:[0,0,1]
	v_pk_fma_f32 v[12:13], v[52:53], v[50:51], v[16:17] op_sel_hi:[1,0,1]
	s_nop 0
	v_mov_b32_e32 v57, v13
	ds_write_b64 v54, v[56:57] offset:14336
	v_add_u32_e32 v9, 0x4000, v9
	s_cbranch_scc0 .LBB0_476
; template <int R, bool INV>
; DEV void fft_pass(cf* buf, int s_log2, int tid) {
;   constexpr int RAD = 1 << R;
;   const int s = 1 << s_log2;
;   const int ngroups = FFT_N >> R;
;   for (int gi = tid; gi < ngroups; gi += 256) {
;     int hi = gi >> s_log2, lo = gi & (s - 1);
;     int base = (hi << (s_log2 + R)) + lo;
;     cf v[RAD];
; #pragma unroll
;     for (int k = 0; k < RAD; ++k) v[k] = buf[fphys(base + (k << s_log2))];
; DEV void hyena_item(const Params& p, int layer, int item, char* smem) {
;     ...
;   __syncthreads();
;   fft_inv(buf, tid);
	s_waitcnt lgkmcnt(0)
	s_barrier
	s_and_saveexec_b64 s[34:35], s[2:3]
	s_cbranch_execz .LBB0_487
	v_add_u32_e32 v9, 0xff, v65
	s_movk_i32 s0, 0x2100
	s_movk_i32 s4, 0x20ff
	v_cmp_gt_u32_e64 s[0:1], s0, v9
	v_cmp_lt_u32_e64 s[4:5], s4, v9
	v_mov_b32_e32 v10, v8
	s_and_saveexec_b64 s[20:21], s[4:5]
	s_cbranch_execz .LBB0_484
	v_lshrrev_b32_e32 v9, 8, v9
	s_movk_i32 s4, 0x48
	v_mul_lo_u32 v10, v8, s4
	v_mul_hi_u32_u24_e32 v11, 0x4800, v9
	s_movk_i32 s6, 0x4800
	v_cmp_ne_u32_e64 s[4:5], 0, v11
	v_mad_u32_u24 v11, v9, s6, v10
	v_cmp_lt_u32_e64 s[6:7], v11, v10
	v_add_u32_e32 v12, 8, v10
	v_add_u32_e32 v13, 8, v11
	s_or_b64 s[22:23], s[6:7], s[4:5]
	v_cmp_lt_u32_e64 s[6:7], v13, v12
	v_add_u32_e32 v12, 12, v10
	v_add_u32_e32 v13, 12, v11
	s_or_b64 s[24:25], s[6:7], s[4:5]
	v_cmp_lt_u32_e64 s[6:7], v13, v12
	v_add_u32_e32 v12, 16, v10
	v_add_u32_e32 v13, 16, v11
	s_or_b64 s[28:29], s[6:7], s[4:5]
	v_cmp_lt_u32_e64 s[6:7], v13, v12
	v_add_u32_e32 v12, 20, v10
	v_add_u32_e32 v13, 20, v11
	s_or_b64 s[30:31], s[6:7], s[4:5]
	v_cmp_lt_u32_e64 s[6:7], v13, v12
	v_add_u32_e32 v12, 24, v10
	v_add_u32_e32 v13, 24, v11
	s_or_b64 s[36:37], s[6:7], s[4:5]
	v_cmp_lt_u32_e64 s[6:7], v13, v12
	v_add_u32_e32 v12, 28, v10
	v_add_u32_e32 v13, 28, v11
	s_or_b64 s[38:39], s[6:7], s[4:5]
	v_cmp_lt_u32_e64 s[6:7], v13, v12
	v_add_u32_e32 v12, 32, v10
	v_add_u32_e32 v13, 32, v11
	s_or_b64 s[40:41], s[6:7], s[4:5]
	v_cmp_lt_u32_e64 s[6:7], v13, v12
	v_add_u32_e32 v12, 36, v10
	v_add_u32_e32 v13, 36, v11
	s_or_b64 s[42:43], s[6:7], s[4:5]
	v_cmp_lt_u32_e64 s[6:7], v13, v12
	v_add_u32_e32 v12, 40, v10
	v_add_u32_e32 v13, 40, v11
	s_or_b64 s[44:45], s[6:7], s[4:5]
	v_cmp_lt_u32_e64 s[6:7], v13, v12
	v_add_u32_e32 v12, 44, v10
	v_add_u32_e32 v13, 44, v11
	s_or_b64 s[46:47], s[6:7], s[4:5]
	v_cmp_lt_u32_e64 s[6:7], v13, v12
	v_add_u32_e32 v12, 48, v10
	v_add_u32_e32 v13, 48, v11
	s_or_b64 s[48:49], s[6:7], s[4:5]
	v_cmp_lt_u32_e64 s[6:7], v13, v12
	v_add_u32_e32 v12, 52, v10
	v_add_u32_e32 v13, 52, v11
	s_or_b64 s[50:51], s[6:7], s[4:5]
	v_cmp_lt_u32_e64 s[6:7], v13, v12
	v_add_u32_e32 v12, 56, v10
	v_add_u32_e32 v13, 56, v11
	s_or_b64 s[60:61], s[6:7], s[4:5]
	v_cmp_lt_u32_e64 s[6:7], v13, v12
	v_add_u32_e32 v10, 60, v10
	v_add_u32_e32 v11, 60, v11
	s_or_b64 s[96:97], s[6:7], s[4:5]
	v_cmp_lt_u32_e64 s[6:7], v11, v10
	s_or_b64 s[4:5], s[6:7], s[4:5]
	s_or_b64 s[6:7], s[22:23], s[24:25]
	s_or_b64 s[6:7], s[6:7], s[28:29]
	s_or_b64 s[6:7], s[6:7], s[30:31]
	s_or_b64 s[6:7], s[6:7], s[36:37]
	s_or_b64 s[6:7], s[6:7], s[38:39]
	s_or_b64 s[6:7], s[6:7], s[40:41]
	s_or_b64 s[6:7], s[6:7], s[42:43]
	s_or_b64 s[6:7], s[6:7], s[44:45]
	s_or_b64 s[6:7], s[6:7], s[46:47]
	s_or_b64 s[6:7], s[6:7], s[48:49]
	s_or_b64 s[6:7], s[6:7], s[50:51]
	s_or_b64 s[6:7], s[6:7], s[60:61]
	s_or_b64 s[6:7], s[6:7], s[96:97]
	s_nor_b64 s[22:23], s[6:7], s[4:5]
	s_mov_b64 s[4:5], -1
	v_mov_b32_e32 v10, v8
	s_and_saveexec_b64 s[6:7], s[22:23]
	s_cbranch_execz .LBB0_483
	v_add_u32_e32 v44, 1, v9
	v_and_b32_e32 v45, 0x1fffffe, v44
	v_add_u32_e32 v9, 0x100, v8
	s_mov_b64 s[22:23], 0
	v_mov_b32_e32 v46, v45
	v_mov_b64_e32 v[10:11], v[8:9]
